# write-through (sc1) stores for the SwiGLU epilogue output (hid), so the seam barrier finds no dirty L2 lines
# speedup vs baseline: 1.0050x; 1.0050x over previous
; __device__ __forceinline__ unsigned cvt_pk_bf16(float lo, float hi) { const f32x2 v = {lo, hi}; return __builtin_bit_cast(unsigned, __builtin_convertvector(v, bf16v2_t)); }
; __device__ __forceinline__ float silu_f(float v) { return v * __builtin_amdgcn_rcpf(1.0f + fexp(-v)); }
;     __device__ __forceinline__ void operator()(const f32x4 (&acc)[2][2][4][2], const pg8::Unit& u, int wr, int wc, int fr, int fq) const {
;     ...
;             for (int m = 0; m < 4; ++m) { u32x4 w;
; #pragma unroll
;                 for (int n = 0; n < 2; ++n) { const f32x4 a = acc[ai][0][m][n], b = acc[ai][1][m][n];
;                     w[2 * n] = cvt_pk_bf16(silu_f(a[0]) * b[0], silu_f(a[1]) * b[1]); w[2 * n + 1] = cvt_pk_bf16(silu_f(a[2]) * b[2], silu_f(a[3]) * b[3]); }
;                 const int row = row0 + ai * 128 + m * 16;
;                 *(u32x4*)(hid + ((size_t)((row >> 8) * (DFF / 64) + (hc0 >> 6)) * 2 + ((row >> 7) & 1)) * 8192 + (row & 127) * 64 + (hc0 & 63)) = w; }
.LBB0_614:
	v_mov_b32_e32 v214, 0xbfb8aa3b
	v_mov_b32_e32 v215, 0xbfb8aa3b
	v_pk_mul_f32 v[206:207], v[126:127], v[214:215] op_sel_hi:[1,0]
	v_pk_mul_f32 v[208:209], v[128:129], v[214:215] op_sel_hi:[1,0]
	v_pk_mul_f32 v[210:211], v[118:119], v[214:215] op_sel_hi:[1,0]
	v_pk_mul_f32 v[212:213], v[120:121], v[214:215] op_sel_hi:[1,0]
	v_exp_f32_e32 v206, v206
	v_exp_f32_e32 v207, v207
	v_exp_f32_e32 v208, v208
	v_exp_f32_e32 v209, v209
	v_exp_f32_e32 v210, v210
	v_exp_f32_e32 v211, v211
	v_exp_f32_e32 v212, v212
	v_exp_f32_e32 v213, v213
	v_pk_add_f32 v[206:207], v[206:207], 1.0 op_sel_hi:[1,0]
	v_pk_add_f32 v[208:209], v[208:209], 1.0 op_sel_hi:[1,0]
	v_pk_add_f32 v[210:211], v[210:211], 1.0 op_sel_hi:[1,0]
	v_pk_add_f32 v[212:213], v[212:213], 1.0 op_sel_hi:[1,0]
	v_rcp_f32_e32 v206, v206
	v_rcp_f32_e32 v207, v207
	v_rcp_f32_e32 v208, v208
	v_rcp_f32_e32 v209, v209
	v_rcp_f32_e32 v210, v210
	v_rcp_f32_e32 v211, v211
	v_rcp_f32_e32 v212, v212
	v_rcp_f32_e32 v213, v213
	v_pk_mul_f32 v[206:207], v[126:127], v[206:207]
	v_pk_mul_f32 v[208:209], v[128:129], v[208:209]
	v_pk_mul_f32 v[210:211], v[118:119], v[210:211]
	v_pk_mul_f32 v[212:213], v[120:121], v[212:213]
	v_pk_mul_f32 v[206:207], v[206:207], v[122:123]
	v_pk_mul_f32 v[208:209], v[208:209], v[124:125]
	v_pk_mul_f32 v[210:211], v[210:211], v[114:115]
	v_pk_mul_f32 v[212:213], v[212:213], v[116:117]
	v_cvt_pk_bf16_f32 v122, v206, v207
	v_cvt_pk_bf16_f32 v123, v208, v209
	v_cvt_pk_bf16_f32 v124, v210, v211
	v_cvt_pk_bf16_f32 v125, v212, v213
	s_lshl_b32 s13, s18, 8
	s_add_i32 s13, s13, s38
	s_lshl_b32 s11, s19, 7
	s_or_b32 s11, s11, s39
	s_ashr_i32 s18, s13, 8
	s_ashr_i32 s11, s11, 6
	s_mul_i32 s18, s18, 44
	s_add_i32 s18, s18, s11
	s_ashr_i32 s19, s18, 31
	s_lshl_b64 s[18:19], s[18:19], 15
	v_readlane_b32 s20, v249, 53
	v_readlane_b32 s21, v249, 54
	s_add_u32 s18, s20, s18
	v_or_b32_e32 v143, s13, v140
	s_addc_u32 s19, s21, s19
	s_lshl_b32 s13, s13, 7
	s_and_b32 s13, s13, 0x4000
	s_add_u32 s18, s18, s13
	s_addc_u32 s19, s19, 0
	v_mov_b32_e32 v139, v1
	v_lshlrev_b32_e32 v0, 7, v143
	v_and_b32_e32 v0, 0x2780, v0
	s_andn2_b64 vcc, exec, s[0:1]
	v_lshl_add_u64 v[114:115], s[18:19], 0, v[0:1]
	v_lshl_add_u64 v[114:115], v[114:115], 0, v[138:139]
	global_store_dwordx4 v[114:115], v[122:125], off sc1
	v_pk_mul_f32 v[206:207], v[110:111], v[214:215] op_sel_hi:[1,0]
	v_pk_mul_f32 v[208:209], v[112:113], v[214:215] op_sel_hi:[1,0]
	v_pk_mul_f32 v[210:211], v[102:103], v[214:215] op_sel_hi:[1,0]
	v_pk_mul_f32 v[212:213], v[104:105], v[214:215] op_sel_hi:[1,0]
	v_exp_f32_e32 v206, v206
	v_exp_f32_e32 v207, v207
	v_exp_f32_e32 v208, v208
	v_exp_f32_e32 v209, v209
	v_exp_f32_e32 v210, v210
	v_exp_f32_e32 v211, v211
	v_exp_f32_e32 v212, v212
	v_exp_f32_e32 v213, v213
	v_pk_add_f32 v[206:207], v[206:207], 1.0 op_sel_hi:[1,0]
	v_pk_add_f32 v[208:209], v[208:209], 1.0 op_sel_hi:[1,0]
	v_pk_add_f32 v[210:211], v[210:211], 1.0 op_sel_hi:[1,0]
	v_pk_add_f32 v[212:213], v[212:213], 1.0 op_sel_hi:[1,0]
	v_rcp_f32_e32 v206, v206
	v_rcp_f32_e32 v207, v207
	v_rcp_f32_e32 v208, v208
	v_rcp_f32_e32 v209, v209
	v_rcp_f32_e32 v210, v210
	v_rcp_f32_e32 v211, v211
	v_rcp_f32_e32 v212, v212
	v_rcp_f32_e32 v213, v213
	v_pk_mul_f32 v[206:207], v[110:111], v[206:207]
	v_pk_mul_f32 v[208:209], v[112:113], v[208:209]
	v_pk_mul_f32 v[210:211], v[102:103], v[210:211]
	v_pk_mul_f32 v[212:213], v[104:105], v[212:213]
	v_pk_mul_f32 v[206:207], v[206:207], v[106:107]
	v_pk_mul_f32 v[208:209], v[208:209], v[108:109]
	v_pk_mul_f32 v[210:211], v[210:211], v[98:99]
	v_pk_mul_f32 v[212:213], v[212:213], v[100:101]
	v_cvt_pk_bf16_f32 v106, v206, v207
	v_cvt_pk_bf16_f32 v107, v208, v209
	v_cvt_pk_bf16_f32 v108, v210, v211
	v_cvt_pk_bf16_f32 v109, v212, v213
	global_store_dwordx4 v[114:115], v[106:109], off offset:2048 sc1
	v_pk_mul_f32 v[206:207], v[94:95], v[214:215] op_sel_hi:[1,0]
	v_pk_mul_f32 v[208:209], v[96:97], v[214:215] op_sel_hi:[1,0]
	v_pk_mul_f32 v[210:211], v[86:87], v[214:215] op_sel_hi:[1,0]
	v_pk_mul_f32 v[212:213], v[88:89], v[214:215] op_sel_hi:[1,0]
	v_exp_f32_e32 v206, v206
	v_exp_f32_e32 v207, v207
	v_exp_f32_e32 v208, v208
	v_exp_f32_e32 v209, v209
	v_exp_f32_e32 v210, v210
	v_exp_f32_e32 v211, v211
	v_exp_f32_e32 v212, v212
	v_exp_f32_e32 v213, v213
	v_pk_add_f32 v[206:207], v[206:207], 1.0 op_sel_hi:[1,0]
	v_pk_add_f32 v[208:209], v[208:209], 1.0 op_sel_hi:[1,0]
	v_pk_add_f32 v[210:211], v[210:211], 1.0 op_sel_hi:[1,0]
	v_pk_add_f32 v[212:213], v[212:213], 1.0 op_sel_hi:[1,0]
	v_rcp_f32_e32 v206, v206
	v_rcp_f32_e32 v207, v207
	v_rcp_f32_e32 v208, v208
	v_rcp_f32_e32 v209, v209
	v_rcp_f32_e32 v210, v210
	v_rcp_f32_e32 v211, v211
	v_rcp_f32_e32 v212, v212
	v_rcp_f32_e32 v213, v213
	v_pk_mul_f32 v[206:207], v[94:95], v[206:207]
	v_pk_mul_f32 v[208:209], v[96:97], v[208:209]
	v_pk_mul_f32 v[210:211], v[86:87], v[210:211]
	v_pk_mul_f32 v[212:213], v[88:89], v[212:213]
	v_pk_mul_f32 v[206:207], v[206:207], v[90:91]
	v_pk_mul_f32 v[208:209], v[208:209], v[92:93]
	v_pk_mul_f32 v[210:211], v[210:211], v[82:83]
	v_pk_mul_f32 v[212:213], v[212:213], v[84:85]
	v_cvt_pk_bf16_f32 v90, v206, v207
	v_cvt_pk_bf16_f32 v91, v208, v209
	v_cvt_pk_bf16_f32 v92, v210, v211
	v_cvt_pk_bf16_f32 v93, v212, v213
	v_or_b32_e32 v82, 0x1000, v0
	v_mov_b32_e32 v83, v1
	v_lshl_add_u64 v[84:85], s[18:19], 0, v[82:83]
	v_lshl_add_u64 v[84:85], v[84:85], 0, v[138:139]
	global_store_dwordx4 v[84:85], v[90:93], off sc1
	v_pk_mul_f32 v[206:207], v[78:79], v[214:215] op_sel_hi:[1,0]
	v_pk_mul_f32 v[208:209], v[80:81], v[214:215] op_sel_hi:[1,0]
	v_pk_mul_f32 v[210:211], v[70:71], v[214:215] op_sel_hi:[1,0]
	v_pk_mul_f32 v[212:213], v[72:73], v[214:215] op_sel_hi:[1,0]
; __device__ __forceinline__ unsigned cvt_pk_bf16(float lo, float hi) { const f32x2 v = {lo, hi}; return __builtin_bit_cast(unsigned, __builtin_convertvector(v, bf16v2_t)); }
; __device__ __forceinline__ float silu_f(float v) { return v * __builtin_amdgcn_rcpf(1.0f + fexp(-v)); }
;     __device__ __forceinline__ void operator()(const f32x4 (&acc)[2][2][4][2], const pg8::Unit& u, int wr, int wc, int fr, int fq) const {
;     ...
;             for (int m = 0; m < 4; ++m) { u32x4 w;
; #pragma unroll
;                 for (int n = 0; n < 2; ++n) { const f32x4 a = acc[ai][0][m][n], b = acc[ai][1][m][n];
;                     w[2 * n] = cvt_pk_bf16(silu_f(a[0]) * b[0], silu_f(a[1]) * b[1]); w[2 * n + 1] = cvt_pk_bf16(silu_f(a[2]) * b[2], silu_f(a[3]) * b[3]); }
;                 const int row = row0 + ai * 128 + m * 16;
;                 *(u32x4*)(hid + ((size_t)((row >> 8) * (DFF / 64) + (hc0 >> 6)) * 2 + ((row >> 7) & 1)) * 8192 + (row & 127) * 64 + (hc0 & 63)) = w; }
	v_exp_f32_e32 v206, v206
	v_exp_f32_e32 v207, v207
	v_exp_f32_e32 v208, v208
	v_exp_f32_e32 v209, v209
	v_exp_f32_e32 v210, v210
	v_exp_f32_e32 v211, v211
	v_exp_f32_e32 v212, v212
	v_exp_f32_e32 v213, v213
	v_pk_add_f32 v[206:207], v[206:207], 1.0 op_sel_hi:[1,0]
	v_pk_add_f32 v[208:209], v[208:209], 1.0 op_sel_hi:[1,0]
	v_pk_add_f32 v[210:211], v[210:211], 1.0 op_sel_hi:[1,0]
	v_pk_add_f32 v[212:213], v[212:213], 1.0 op_sel_hi:[1,0]
	v_rcp_f32_e32 v206, v206
	v_rcp_f32_e32 v207, v207
	v_rcp_f32_e32 v208, v208
	v_rcp_f32_e32 v209, v209
	v_rcp_f32_e32 v210, v210
	v_rcp_f32_e32 v211, v211
	v_rcp_f32_e32 v212, v212
	v_rcp_f32_e32 v213, v213
	v_pk_mul_f32 v[206:207], v[78:79], v[206:207]
	v_pk_mul_f32 v[208:209], v[80:81], v[208:209]
	v_pk_mul_f32 v[210:211], v[70:71], v[210:211]
	v_pk_mul_f32 v[212:213], v[72:73], v[212:213]
	v_pk_mul_f32 v[206:207], v[206:207], v[74:75]
	v_pk_mul_f32 v[208:209], v[208:209], v[76:77]
	v_pk_mul_f32 v[210:211], v[210:211], v[66:67]
	v_pk_mul_f32 v[212:213], v[212:213], v[68:69]
	v_cvt_pk_bf16_f32 v74, v206, v207
	v_cvt_pk_bf16_f32 v75, v208, v209
	v_cvt_pk_bf16_f32 v76, v210, v211
	v_cvt_pk_bf16_f32 v77, v212, v213
	v_add_u32_e32 v72, 0x80, v143
	v_or_b32_e32 v66, 0x1800, v0
	v_mov_b32_e32 v67, v1
	v_lshl_add_u64 v[68:69], s[18:19], 0, v[66:67]
	v_lshl_add_u64 v[68:69], v[68:69], 0, v[138:139]
	global_store_dwordx4 v[68:69], v[74:77], off sc1
	v_pk_mul_f32 v[206:207], v[62:63], v[214:215] op_sel_hi:[1,0]
	v_pk_mul_f32 v[208:209], v[64:65], v[214:215] op_sel_hi:[1,0]
	v_pk_mul_f32 v[210:211], v[54:55], v[214:215] op_sel_hi:[1,0]
	v_pk_mul_f32 v[212:213], v[56:57], v[214:215] op_sel_hi:[1,0]
	v_exp_f32_e32 v206, v206
	v_exp_f32_e32 v207, v207
	v_exp_f32_e32 v208, v208
	v_exp_f32_e32 v209, v209
	v_exp_f32_e32 v210, v210
	v_exp_f32_e32 v211, v211
	v_exp_f32_e32 v212, v212
	v_exp_f32_e32 v213, v213
	v_pk_add_f32 v[206:207], v[206:207], 1.0 op_sel_hi:[1,0]
	v_pk_add_f32 v[208:209], v[208:209], 1.0 op_sel_hi:[1,0]
	v_pk_add_f32 v[210:211], v[210:211], 1.0 op_sel_hi:[1,0]
	v_pk_add_f32 v[212:213], v[212:213], 1.0 op_sel_hi:[1,0]
	v_rcp_f32_e32 v206, v206
	v_rcp_f32_e32 v207, v207
	v_rcp_f32_e32 v208, v208
	v_rcp_f32_e32 v209, v209
	v_rcp_f32_e32 v210, v210
	v_rcp_f32_e32 v211, v211
	v_rcp_f32_e32 v212, v212
	v_rcp_f32_e32 v213, v213
	v_pk_mul_f32 v[206:207], v[62:63], v[206:207]
	v_pk_mul_f32 v[208:209], v[64:65], v[208:209]
	v_pk_mul_f32 v[210:211], v[54:55], v[210:211]
	v_pk_mul_f32 v[212:213], v[56:57], v[212:213]
	v_pk_mul_f32 v[206:207], v[206:207], v[58:59]
	v_pk_mul_f32 v[208:209], v[208:209], v[60:61]
	v_pk_mul_f32 v[210:211], v[210:211], v[50:51]
	v_pk_mul_f32 v[212:213], v[212:213], v[52:53]
	v_cvt_pk_bf16_f32 v58, v206, v207
	v_cvt_pk_bf16_f32 v59, v208, v209
	v_cvt_pk_bf16_f32 v60, v210, v211
	v_cvt_pk_bf16_f32 v61, v212, v213
	v_lshrrev_b32_e32 v68, 8, v72
	v_mad_i32_i24 v68, v68, 44, s11
	v_ashrrev_i32_e32 v69, 31, v68
	v_lshlrev_b64 v[68:69], 15, v[68:69]
	s_mov_b64 s[18:19], -1
	v_lshlrev_b32_e32 v52, 7, v72
	v_lshl_add_u64 v[50:51], s[20:21], 0, v[68:69]
	v_and_b32_e32 v52, 0x4000, v52
	v_mov_b32_e32 v53, v1
	v_lshl_add_u64 v[50:51], v[50:51], 0, v[52:53]
	v_lshl_add_u64 v[52:53], v[50:51], 0, v[0:1]
	v_lshl_add_u64 v[52:53], v[52:53], 0, v[138:139]
	global_store_dwordx4 v[52:53], v[58:61], off sc1
	v_pk_mul_f32 v[206:207], v[46:47], v[214:215] op_sel_hi:[1,0]
	v_pk_mul_f32 v[208:209], v[48:49], v[214:215] op_sel_hi:[1,0]
	v_pk_mul_f32 v[210:211], v[38:39], v[214:215] op_sel_hi:[1,0]
	v_pk_mul_f32 v[212:213], v[40:41], v[214:215] op_sel_hi:[1,0]
	v_exp_f32_e32 v206, v206
	v_exp_f32_e32 v207, v207
	v_exp_f32_e32 v208, v208
	v_exp_f32_e32 v209, v209
	v_exp_f32_e32 v210, v210
	v_exp_f32_e32 v211, v211
	v_exp_f32_e32 v212, v212
	v_exp_f32_e32 v213, v213
	v_pk_add_f32 v[206:207], v[206:207], 1.0 op_sel_hi:[1,0]
	v_pk_add_f32 v[208:209], v[208:209], 1.0 op_sel_hi:[1,0]
	v_pk_add_f32 v[210:211], v[210:211], 1.0 op_sel_hi:[1,0]
	v_pk_add_f32 v[212:213], v[212:213], 1.0 op_sel_hi:[1,0]
; __device__ __forceinline__ unsigned cvt_pk_bf16(float lo, float hi) { const f32x2 v = {lo, hi}; return __builtin_bit_cast(unsigned, __builtin_convertvector(v, bf16v2_t)); }
; __device__ __forceinline__ float silu_f(float v) { return v * __builtin_amdgcn_rcpf(1.0f + fexp(-v)); }
; #define PG8_BAR __builtin_amdgcn_s_barrier()
; template <class Epi, bool ALIGN_EPI = PG8_ALIGN, bool SP2 = PG8_SP2>
; __device__ __forceinline__ void gemm_phase(LAS unsigned char* lds, const Gemm g, const StaticOrder& S, const Epi& E) {
;     ...
;         if (!has_next) break;
; #pragma unroll
;         for (int a = 0; a < 2; ++a)
; #pragma unroll
;             for (int b = 0; b < 2; ++b)
; #pragma unroll
;                 for (int m = 0; m < 4; ++m)
; #pragma unroll
;                     for (int n = 0; n < 2; ++n) acc[a][b][m][n] = (f32x4){0.f, 0.f, 0.f, 0.f};
;         cur = nxt; cA = nA; cB = nB; ++ui;
;         if constexpr (ALIGN_EPI) { if (wr == 1) PG8_BAR; }
;     __device__ __forceinline__ void operator()(const f32x4 (&acc)[2][2][4][2], const pg8::Unit& u, int wr, int wc, int fr, int fq) const {
;     ...
;             for (int m = 0; m < 4; ++m) { u32x4 w;
; #pragma unroll
;                 for (int n = 0; n < 2; ++n) { const f32x4 a = acc[ai][0][m][n], b = acc[ai][1][m][n];
;                     w[2 * n] = cvt_pk_bf16(silu_f(a[0]) * b[0], silu_f(a[1]) * b[1]); w[2 * n + 1] = cvt_pk_bf16(silu_f(a[2]) * b[2], silu_f(a[3]) * b[3]); }
;                 const int row = row0 + ai * 128 + m * 16;
;                 *(u32x4*)(hid + ((size_t)((row >> 8) * (DFF / 64) + (hc0 >> 6)) * 2 + ((row >> 7) & 1)) * 8192 + (row & 127) * 64 + (hc0 & 63)) = w; }
	v_rcp_f32_e32 v206, v206
	v_rcp_f32_e32 v207, v207
	v_rcp_f32_e32 v208, v208
	v_rcp_f32_e32 v209, v209
	v_rcp_f32_e32 v210, v210
	v_rcp_f32_e32 v211, v211
	v_rcp_f32_e32 v212, v212
	v_rcp_f32_e32 v213, v213
	v_pk_mul_f32 v[206:207], v[46:47], v[206:207]
	v_pk_mul_f32 v[208:209], v[48:49], v[208:209]
	v_pk_mul_f32 v[210:211], v[38:39], v[210:211]
	v_pk_mul_f32 v[212:213], v[40:41], v[212:213]
	v_pk_mul_f32 v[206:207], v[206:207], v[42:43]
	v_pk_mul_f32 v[208:209], v[208:209], v[44:45]
	v_pk_mul_f32 v[210:211], v[210:211], v[34:35]
	v_pk_mul_f32 v[212:213], v[212:213], v[36:37]
	v_cvt_pk_bf16_f32 v42, v206, v207
	v_cvt_pk_bf16_f32 v43, v208, v209
	v_cvt_pk_bf16_f32 v44, v210, v211
	v_cvt_pk_bf16_f32 v45, v212, v213
	global_store_dwordx4 v[52:53], v[42:45], off offset:2048 sc1
	v_pk_mul_f32 v[206:207], v[30:31], v[214:215] op_sel_hi:[1,0]
	v_pk_mul_f32 v[208:209], v[32:33], v[214:215] op_sel_hi:[1,0]
	v_pk_mul_f32 v[210:211], v[22:23], v[214:215] op_sel_hi:[1,0]
	v_pk_mul_f32 v[212:213], v[24:25], v[214:215] op_sel_hi:[1,0]
	v_exp_f32_e32 v206, v206
	v_exp_f32_e32 v207, v207
	v_exp_f32_e32 v208, v208
	v_exp_f32_e32 v209, v209
	v_exp_f32_e32 v210, v210
	v_exp_f32_e32 v211, v211
	v_exp_f32_e32 v212, v212
	v_exp_f32_e32 v213, v213
	v_pk_add_f32 v[206:207], v[206:207], 1.0 op_sel_hi:[1,0]
	v_pk_add_f32 v[208:209], v[208:209], 1.0 op_sel_hi:[1,0]
	v_pk_add_f32 v[210:211], v[210:211], 1.0 op_sel_hi:[1,0]
	v_pk_add_f32 v[212:213], v[212:213], 1.0 op_sel_hi:[1,0]
	v_rcp_f32_e32 v206, v206
	v_rcp_f32_e32 v207, v207
	v_rcp_f32_e32 v208, v208
	v_rcp_f32_e32 v209, v209
	v_rcp_f32_e32 v210, v210
	v_rcp_f32_e32 v211, v211
	v_rcp_f32_e32 v212, v212
	v_rcp_f32_e32 v213, v213
	v_pk_mul_f32 v[206:207], v[30:31], v[206:207]
	v_pk_mul_f32 v[208:209], v[32:33], v[208:209]
	v_pk_mul_f32 v[210:211], v[22:23], v[210:211]
	v_pk_mul_f32 v[212:213], v[24:25], v[212:213]
	v_pk_mul_f32 v[206:207], v[206:207], v[26:27]
	v_pk_mul_f32 v[208:209], v[208:209], v[28:29]
	v_pk_mul_f32 v[210:211], v[210:211], v[18:19]
	v_pk_mul_f32 v[212:213], v[212:213], v[20:21]
	v_cvt_pk_bf16_f32 v26, v206, v207
	v_cvt_pk_bf16_f32 v27, v208, v209
	v_cvt_pk_bf16_f32 v28, v210, v211
	v_cvt_pk_bf16_f32 v29, v212, v213
	v_lshl_add_u64 v[18:19], v[50:51], 0, v[82:83]
	v_lshl_add_u64 v[18:19], v[18:19], 0, v[138:139]
	global_store_dwordx4 v[18:19], v[26:29], off sc1
	v_pk_mul_f32 v[206:207], v[14:15], v[214:215] op_sel_hi:[1,0]
	v_pk_mul_f32 v[208:209], v[16:17], v[214:215] op_sel_hi:[1,0]
	v_pk_mul_f32 v[210:211], v[6:7], v[214:215] op_sel_hi:[1,0]
	v_pk_mul_f32 v[212:213], v[8:9], v[214:215] op_sel_hi:[1,0]
	v_exp_f32_e32 v206, v206
	v_exp_f32_e32 v207, v207
	v_exp_f32_e32 v208, v208
	v_exp_f32_e32 v209, v209
	v_exp_f32_e32 v210, v210
	v_exp_f32_e32 v211, v211
	v_exp_f32_e32 v212, v212
	v_exp_f32_e32 v213, v213
	v_pk_add_f32 v[206:207], v[206:207], 1.0 op_sel_hi:[1,0]
	v_pk_add_f32 v[208:209], v[208:209], 1.0 op_sel_hi:[1,0]
	v_pk_add_f32 v[210:211], v[210:211], 1.0 op_sel_hi:[1,0]
	v_pk_add_f32 v[212:213], v[212:213], 1.0 op_sel_hi:[1,0]
	v_rcp_f32_e32 v206, v206
	v_rcp_f32_e32 v207, v207
	v_rcp_f32_e32 v208, v208
	v_rcp_f32_e32 v209, v209
	v_rcp_f32_e32 v210, v210
	v_rcp_f32_e32 v211, v211
	v_rcp_f32_e32 v212, v212
	v_rcp_f32_e32 v213, v213
	v_pk_mul_f32 v[206:207], v[14:15], v[206:207]
	v_pk_mul_f32 v[208:209], v[16:17], v[208:209]
	v_pk_mul_f32 v[210:211], v[6:7], v[210:211]
	v_pk_mul_f32 v[212:213], v[8:9], v[212:213]
	v_pk_mul_f32 v[206:207], v[206:207], v[10:11]
	v_pk_mul_f32 v[208:209], v[208:209], v[12:13]
	v_pk_mul_f32 v[210:211], v[210:211], v[2:3]
	v_pk_mul_f32 v[212:213], v[212:213], v[4:5]
	v_cvt_pk_bf16_f32 v10, v206, v207
	v_cvt_pk_bf16_f32 v11, v208, v209
	v_cvt_pk_bf16_f32 v12, v210, v211
	v_cvt_pk_bf16_f32 v13, v212, v213
	v_lshl_add_u64 v[2:3], v[50:51], 0, v[66:67]
	v_lshl_add_u64 v[2:3], v[2:3], 0, v[138:139]
	global_store_dwordx4 v[2:3], v[10:13], off sc1
	s_cbranch_vccnz .LBB0_603
	s_andn2_b64 vcc, exec, s[6:7]
	s_cbranch_vccnz .LBB0_602
	s_barrier
	s_branch .LBB0_602
